# nt policy also on the P1 gate-level (u8) output stores, consumed only in P5
# baseline (speedup 1.0000x reference)
.LBB0_190:
	v_lshl_add_u32 v162, s40, 8, v161
	v_ashrrev_i32_e32 v163, 31, v162
	v_lshlrev_b64 v[176:177], 11, v[162:163]
	s_waitcnt vmcnt(0)
	v_pk_add_f32 v[168:169], v[136:137], v[72:73]
	v_lshl_add_u64 v[136:137], s[14:15], 0, v[176:177]
	v_pk_add_f32 v[142:143], v[142:143], v[78:79]
	v_pk_add_f32 v[166:167], v[140:141], v[76:77]
	v_pk_add_f32 v[164:165], v[138:139], v[74:75]
	s_and_b64 vcc, exec, s[0:1]
	v_lshl_add_u64 v[138:139], v[136:137], 0, v[158:159]
	s_cbranch_vccnz .LBB0_192
	v_mul_f32_e32 v140, 0xbfb8aa3b, v167
	v_mul_f32_e32 v141, 0xbfb8aa3b, v169
	v_mul_f32_e32 v175, 0xbfb8aa3b, v142
	v_mul_f32_e32 v136, 0xbfb8aa3b, v166
	v_mul_f32_e32 v137, 0xbfb8aa3b, v168
	v_exp_f32_e32 v140, v140
	v_exp_f32_e32 v141, v141
	v_exp_f32_e32 v175, v175
	v_mul_f32_e32 v176, 0xbfb8aa3b, v164
	v_exp_f32_e32 v136, v136
	v_exp_f32_e32 v137, v137
	v_exp_f32_e32 v177, v176
	v_add_f32_e32 v140, 1.0, v140
	v_add_f32_e32 v141, 1.0, v141
	v_add_f32_e32 v175, 1.0, v175
	v_add_f32_e32 v136, 1.0, v136
	v_add_f32_e32 v137, 1.0, v137
	v_rcp_f32_e32 v140, v140
	v_rcp_f32_e32 v141, v141
	v_rcp_f32_e32 v176, v175
	v_add_f32_e32 v175, 1.0, v177
	v_mul_f32_e32 v177, 0xbfb8aa3b, v143
	v_rcp_f32_e32 v136, v136
	v_rcp_f32_e32 v137, v137
	v_exp_f32_e32 v178, v177
	v_mul_f32_e32 v177, 0xbfb8aa3b, v165
	v_exp_f32_e32 v179, v177
	v_pk_fma_f32 v[140:141], v[140:141], s[24:25], 0.5 op_sel_hi:[1,0,0]
	v_rcp_f32_e32 v177, v175
	v_add_f32_e32 v175, 1.0, v178
	v_pk_fma_f32 v[136:137], v[136:137], s[24:25], 0.5 op_sel_hi:[1,0,0]
	v_cvt_u32_f32_e32 v141, v141
	v_cvt_u32_f32_e32 v140, v140
	v_rcp_f32_e32 v178, v175
	v_add_f32_e32 v175, 1.0, v179
	v_cvt_u32_f32_e32 v137, v137
	v_cvt_u32_f32_e32 v136, v136
	v_rcp_f32_e32 v179, v175
	v_lshlrev_b32_e32 v141, 8, v141
	v_lshlrev_b32_e32 v140, 8, v140
	v_or_b32_e32 v141, v141, v137
	v_or_b32_e32 v140, v140, v136
	v_pk_fma_f32 v[136:137], v[176:177], s[24:25], 0.5 op_sel_hi:[1,0,0]
	s_mov_b64 s[40:41], 0
	v_cvt_u32_f32_sdwa v175, v136 dst_sel:WORD_1 dst_unused:UNUSED_PAD src0_sel:DWORD
	v_cvt_u32_f32_sdwa v176, v137 dst_sel:WORD_1 dst_unused:UNUSED_PAD src0_sel:DWORD
	v_pk_fma_f32 v[136:137], v[178:179], s[24:25], 0.5 op_sel_hi:[1,0,0]
	v_or_b32_e32 v140, v140, v175
	v_cvt_u32_f32_sdwa v137, v137 dst_sel:BYTE_3 dst_unused:UNUSED_PAD src0_sel:DWORD
	v_cvt_u32_f32_sdwa v136, v136 dst_sel:BYTE_3 dst_unused:UNUSED_PAD src0_sel:DWORD
	v_or_b32_e32 v141, v141, v176
	v_or_b32_e32 v137, v141, v137
	v_or_b32_e32 v136, v140, v136
	global_store_dwordx2 v[138:139], v[136:137], off nt
	s_branch .LBB0_193

.LBB0_195:
	v_pk_add_f32 v[134:135], v[134:135], v[62:63]
	v_pk_add_f32 v[132:133], v[132:133], v[60:61]
	v_pk_add_f32 v[130:131], v[130:131], v[58:59]
	s_and_b64 vcc, exec, s[0:1]
	v_pk_add_f32 v[128:129], v[128:129], v[56:57]
	s_cbranch_vccnz .LBB0_200
	v_mul_f32_e32 v163, 0xbfb8aa3b, v133
	v_exp_f32_e32 v163, v163
	v_mul_f32_e32 v164, 0xbfb8aa3b, v129
	v_exp_f32_e32 v165, v164
	v_mul_f32_e32 v142, 0xbfb8aa3b, v132
	v_add_f32_e32 v163, 1.0, v163
	v_rcp_f32_e32 v164, v163
	v_add_f32_e32 v163, 1.0, v165
	v_mul_f32_e32 v165, 0xbfb8aa3b, v134
	v_exp_f32_e32 v166, v165
	v_mul_f32_e32 v165, 0xbfb8aa3b, v130
	v_exp_f32_e32 v167, v165
	v_mul_f32_e32 v143, 0xbfb8aa3b, v128
	v_exp_f32_e32 v142, v142
	v_exp_f32_e32 v143, v143
	v_rcp_f32_e32 v165, v163
	v_add_f32_e32 v163, 1.0, v166
	v_rcp_f32_e32 v166, v163
	v_add_f32_e32 v163, 1.0, v167
	v_mul_f32_e32 v167, 0xbfb8aa3b, v135
	v_exp_f32_e32 v168, v167
	v_mul_f32_e32 v167, 0xbfb8aa3b, v131
	v_add_f32_e32 v142, 1.0, v142
	v_add_f32_e32 v143, 1.0, v143
	v_exp_f32_e32 v169, v167
	v_rcp_f32_e32 v142, v142
	v_rcp_f32_e32 v143, v143
	v_rcp_f32_e32 v167, v163
	v_add_f32_e32 v163, 1.0, v168
	v_rcp_f32_e32 v168, v163
	v_add_f32_e32 v163, 1.0, v169
	v_pk_fma_f32 v[164:165], v[164:165], s[24:25], 0.5 op_sel_hi:[1,0,0]
	v_rcp_f32_e32 v169, v163
	v_pk_fma_f32 v[142:143], v[142:143], s[24:25], 0.5 op_sel_hi:[1,0,0]
	v_cvt_u32_f32_e32 v163, v165
	v_cvt_u32_f32_e32 v164, v164
	v_cvt_u32_f32_e32 v143, v143
	v_cvt_u32_f32_e32 v142, v142
	v_lshlrev_b32_e32 v163, 8, v163
	v_lshlrev_b32_e32 v164, 8, v164
	v_or_b32_e32 v163, v163, v143
	v_or_b32_e32 v164, v164, v142
	v_pk_fma_f32 v[142:143], v[166:167], s[24:25], 0.5 op_sel_hi:[1,0,0]
	s_nop 0
	v_cvt_u32_f32_sdwa v165, v142 dst_sel:WORD_1 dst_unused:UNUSED_PAD src0_sel:DWORD
	v_cvt_u32_f32_sdwa v166, v143 dst_sel:WORD_1 dst_unused:UNUSED_PAD src0_sel:DWORD
	v_pk_fma_f32 v[142:143], v[168:169], s[24:25], 0.5 op_sel_hi:[1,0,0]
	v_or_b32_e32 v164, v164, v165
	v_cvt_u32_f32_sdwa v143, v143 dst_sel:BYTE_3 dst_unused:UNUSED_PAD src0_sel:DWORD
	v_cvt_u32_f32_sdwa v142, v142 dst_sel:BYTE_3 dst_unused:UNUSED_PAD src0_sel:DWORD
	v_or_b32_e32 v163, v163, v166
	v_or_b32_e32 v143, v163, v143
	v_or_b32_e32 v142, v164, v142
	global_store_dwordx2 v[138:139], v[142:143], off offset:128 nt
	s_cbranch_execnz .LBB0_198

.LBB0_198:
	s_nop 1
	v_or_b32_e32 v132, 16, v162
	v_ashrrev_i32_e32 v133, 31, v132
	v_lshlrev_b64 v[134:135], 11, v[132:133]
	v_pk_add_f32 v[130:131], v[120:121], v[72:73]
	v_lshl_add_u64 v[120:121], s[14:15], 0, v[134:135]
	v_pk_add_f32 v[126:127], v[126:127], v[78:79]
	v_pk_add_f32 v[128:129], v[124:125], v[76:77]
	v_pk_add_f32 v[124:125], v[122:123], v[74:75]
	s_and_b64 vcc, exec, s[0:1]
	v_lshl_add_u64 v[120:121], v[120:121], 0, v[158:159]
	s_cbranch_vccnz .LBB0_201
	v_mul_f32_e32 v134, 0xbfb8aa3b, v129
	v_mul_f32_e32 v135, 0xbfb8aa3b, v131
	v_mul_f32_e32 v122, 0xbfb8aa3b, v128
	v_mul_f32_e32 v123, 0xbfb8aa3b, v130
	v_exp_f32_e32 v134, v134
	v_exp_f32_e32 v135, v135
	v_exp_f32_e32 v122, v122
	v_exp_f32_e32 v123, v123
	v_add_f32_e32 v134, 1.0, v134
	v_add_f32_e32 v135, 1.0, v135
	v_add_f32_e32 v122, 1.0, v122
	v_add_f32_e32 v123, 1.0, v123
	v_rcp_f32_e32 v134, v134
	v_mul_f32_e32 v138, 0xbfb8aa3b, v126
	v_mul_f32_e32 v139, 0xbfb8aa3b, v124
	v_rcp_f32_e32 v135, v135
	v_rcp_f32_e32 v122, v122
	v_rcp_f32_e32 v123, v123
	v_exp_f32_e32 v138, v138
	v_exp_f32_e32 v139, v139
	v_mul_f32_e32 v140, 0xbfb8aa3b, v127
	v_mul_f32_e32 v141, 0xbfb8aa3b, v125
	v_exp_f32_e32 v140, v140
	v_exp_f32_e32 v141, v141
	v_pk_fma_f32 v[134:135], v[134:135], s[24:25], 0.5 op_sel_hi:[1,0,0]
	v_add_f32_e32 v138, 1.0, v138
	v_add_f32_e32 v139, 1.0, v139
	v_pk_fma_f32 v[122:123], v[122:123], s[24:25], 0.5 op_sel_hi:[1,0,0]
	v_cvt_u32_f32_e32 v135, v135
	v_cvt_u32_f32_e32 v134, v134
	v_rcp_f32_e32 v138, v138
	v_rcp_f32_e32 v139, v139
	v_add_f32_e32 v140, 1.0, v140
	v_add_f32_e32 v141, 1.0, v141
	v_cvt_u32_f32_e32 v123, v123
	v_cvt_u32_f32_e32 v122, v122
	v_rcp_f32_e32 v140, v140
	v_rcp_f32_e32 v141, v141
	v_lshlrev_b32_e32 v135, 8, v135
	v_lshlrev_b32_e32 v134, 8, v134
	v_or_b32_e32 v135, v135, v123
	v_or_b32_e32 v134, v134, v122
	v_pk_fma_f32 v[122:123], v[138:139], s[24:25], 0.5 op_sel_hi:[1,0,0]
	s_mov_b64 s[40:41], 0
	v_cvt_u32_f32_sdwa v138, v122 dst_sel:WORD_1 dst_unused:UNUSED_PAD src0_sel:DWORD
	v_cvt_u32_f32_sdwa v139, v123 dst_sel:WORD_1 dst_unused:UNUSED_PAD src0_sel:DWORD
	v_pk_fma_f32 v[122:123], v[140:141], s[24:25], 0.5 op_sel_hi:[1,0,0]
	v_or_b32_e32 v134, v134, v138
	v_cvt_u32_f32_sdwa v123, v123 dst_sel:BYTE_3 dst_unused:UNUSED_PAD src0_sel:DWORD
	v_cvt_u32_f32_sdwa v122, v122 dst_sel:BYTE_3 dst_unused:UNUSED_PAD src0_sel:DWORD
	v_or_b32_e32 v135, v135, v139
	v_or_b32_e32 v123, v135, v123
	v_or_b32_e32 v122, v134, v122
	global_store_dwordx2 v[120:121], v[122:123], off nt
	s_branch .LBB0_202

.LBB0_204:
	v_pk_add_f32 v[118:119], v[118:119], v[62:63]
	v_pk_add_f32 v[116:117], v[116:117], v[60:61]
	v_pk_add_f32 v[114:115], v[114:115], v[58:59]
	s_and_b64 vcc, exec, s[0:1]
	v_pk_add_f32 v[112:113], v[112:113], v[56:57]
	s_cbranch_vccnz .LBB0_209
	v_mul_f32_e32 v126, 0xbfb8aa3b, v117
	v_mul_f32_e32 v127, 0xbfb8aa3b, v113
	v_mul_f32_e32 v124, 0xbfb8aa3b, v116
	v_mul_f32_e32 v125, 0xbfb8aa3b, v112
	v_exp_f32_e32 v126, v126
	v_exp_f32_e32 v127, v127
	v_exp_f32_e32 v124, v124
	v_exp_f32_e32 v125, v125
	v_add_f32_e32 v126, 1.0, v126
	v_add_f32_e32 v127, 1.0, v127
	v_add_f32_e32 v124, 1.0, v124
	v_add_f32_e32 v125, 1.0, v125
	v_rcp_f32_e32 v126, v126
	v_mul_f32_e32 v128, 0xbfb8aa3b, v118
	v_mul_f32_e32 v129, 0xbfb8aa3b, v114
	v_rcp_f32_e32 v127, v127
	v_rcp_f32_e32 v124, v124
	v_rcp_f32_e32 v125, v125
	v_exp_f32_e32 v128, v128
	v_exp_f32_e32 v129, v129
	v_mul_f32_e32 v130, 0xbfb8aa3b, v119
	v_mul_f32_e32 v131, 0xbfb8aa3b, v115
	v_exp_f32_e32 v130, v130
	v_exp_f32_e32 v131, v131
	v_pk_fma_f32 v[126:127], v[126:127], s[24:25], 0.5 op_sel_hi:[1,0,0]
	v_add_f32_e32 v128, 1.0, v128
	v_add_f32_e32 v129, 1.0, v129
	v_pk_fma_f32 v[124:125], v[124:125], s[24:25], 0.5 op_sel_hi:[1,0,0]
	v_cvt_u32_f32_e32 v127, v127
	v_cvt_u32_f32_e32 v126, v126
	v_rcp_f32_e32 v128, v128
	v_rcp_f32_e32 v129, v129
	v_add_f32_e32 v130, 1.0, v130
	v_add_f32_e32 v131, 1.0, v131
	v_cvt_u32_f32_e32 v125, v125
	v_cvt_u32_f32_e32 v124, v124
	v_rcp_f32_e32 v130, v130
	v_rcp_f32_e32 v131, v131
	v_lshlrev_b32_e32 v127, 8, v127
	v_lshlrev_b32_e32 v126, 8, v126
	v_or_b32_e32 v127, v127, v125
	v_or_b32_e32 v126, v126, v124
	v_pk_fma_f32 v[124:125], v[128:129], s[24:25], 0.5 op_sel_hi:[1,0,0]
	s_nop 0
	v_cvt_u32_f32_sdwa v128, v124 dst_sel:WORD_1 dst_unused:UNUSED_PAD src0_sel:DWORD
	v_cvt_u32_f32_sdwa v129, v125 dst_sel:WORD_1 dst_unused:UNUSED_PAD src0_sel:DWORD
	v_pk_fma_f32 v[124:125], v[130:131], s[24:25], 0.5 op_sel_hi:[1,0,0]
	v_or_b32_e32 v126, v126, v128
	v_cvt_u32_f32_sdwa v125, v125 dst_sel:BYTE_3 dst_unused:UNUSED_PAD src0_sel:DWORD
	v_cvt_u32_f32_sdwa v124, v124 dst_sel:BYTE_3 dst_unused:UNUSED_PAD src0_sel:DWORD
	v_or_b32_e32 v127, v127, v129
	v_or_b32_e32 v125, v127, v125
	v_or_b32_e32 v124, v126, v124
	global_store_dwordx2 v[120:121], v[124:125], off offset:128 nt
	s_cbranch_execnz .LBB0_207

.LBB0_207:
	s_nop 1
	v_or_b32_e32 v116, 32, v162
	v_ashrrev_i32_e32 v117, 31, v116
	v_lshlrev_b64 v[118:119], 11, v[116:117]
	v_pk_add_f32 v[114:115], v[104:105], v[72:73]
	v_lshl_add_u64 v[104:105], s[14:15], 0, v[118:119]
	v_pk_add_f32 v[110:111], v[110:111], v[78:79]
	v_pk_add_f32 v[112:113], v[108:109], v[76:77]
	v_pk_add_f32 v[108:109], v[106:107], v[74:75]
	s_and_b64 vcc, exec, s[0:1]
	v_lshl_add_u64 v[104:105], v[104:105], 0, v[158:159]
	s_cbranch_vccnz .LBB0_210
	v_mul_f32_e32 v118, 0xbfb8aa3b, v113
	v_mul_f32_e32 v119, 0xbfb8aa3b, v115
	v_mul_f32_e32 v106, 0xbfb8aa3b, v112
	v_mul_f32_e32 v107, 0xbfb8aa3b, v114
	v_exp_f32_e32 v118, v118
	v_exp_f32_e32 v119, v119
	v_exp_f32_e32 v106, v106
	v_exp_f32_e32 v107, v107
	v_add_f32_e32 v118, 1.0, v118
	v_add_f32_e32 v119, 1.0, v119
	v_add_f32_e32 v106, 1.0, v106
	v_add_f32_e32 v107, 1.0, v107
	v_rcp_f32_e32 v118, v118
	v_mul_f32_e32 v120, 0xbfb8aa3b, v110
	v_mul_f32_e32 v121, 0xbfb8aa3b, v108
	v_rcp_f32_e32 v119, v119
	v_rcp_f32_e32 v106, v106
	v_rcp_f32_e32 v107, v107
	v_exp_f32_e32 v120, v120
	v_exp_f32_e32 v121, v121
	v_mul_f32_e32 v122, 0xbfb8aa3b, v111
	v_mul_f32_e32 v123, 0xbfb8aa3b, v109
	v_exp_f32_e32 v122, v122
	v_exp_f32_e32 v123, v123
	v_pk_fma_f32 v[118:119], v[118:119], s[24:25], 0.5 op_sel_hi:[1,0,0]
	v_add_f32_e32 v120, 1.0, v120
	v_add_f32_e32 v121, 1.0, v121
	v_pk_fma_f32 v[106:107], v[106:107], s[24:25], 0.5 op_sel_hi:[1,0,0]
	v_cvt_u32_f32_e32 v119, v119
	v_cvt_u32_f32_e32 v118, v118
	v_rcp_f32_e32 v120, v120
	v_rcp_f32_e32 v121, v121
	v_add_f32_e32 v122, 1.0, v122
	v_add_f32_e32 v123, 1.0, v123
	v_cvt_u32_f32_e32 v107, v107
	v_cvt_u32_f32_e32 v106, v106
	v_rcp_f32_e32 v122, v122
	v_rcp_f32_e32 v123, v123
	v_lshlrev_b32_e32 v119, 8, v119
	v_lshlrev_b32_e32 v118, 8, v118
	v_or_b32_e32 v119, v119, v107
	v_or_b32_e32 v118, v118, v106
	v_pk_fma_f32 v[106:107], v[120:121], s[24:25], 0.5 op_sel_hi:[1,0,0]
	s_mov_b64 s[40:41], 0
	v_cvt_u32_f32_sdwa v120, v106 dst_sel:WORD_1 dst_unused:UNUSED_PAD src0_sel:DWORD
	v_cvt_u32_f32_sdwa v121, v107 dst_sel:WORD_1 dst_unused:UNUSED_PAD src0_sel:DWORD
	v_pk_fma_f32 v[106:107], v[122:123], s[24:25], 0.5 op_sel_hi:[1,0,0]
	v_or_b32_e32 v118, v118, v120
	v_cvt_u32_f32_sdwa v107, v107 dst_sel:BYTE_3 dst_unused:UNUSED_PAD src0_sel:DWORD
	v_cvt_u32_f32_sdwa v106, v106 dst_sel:BYTE_3 dst_unused:UNUSED_PAD src0_sel:DWORD
	v_or_b32_e32 v119, v119, v121
	v_or_b32_e32 v107, v119, v107
	v_or_b32_e32 v106, v118, v106
	global_store_dwordx2 v[104:105], v[106:107], off nt
	s_branch .LBB0_211

.LBB0_213:
	v_pk_add_f32 v[102:103], v[102:103], v[62:63]
	v_pk_add_f32 v[100:101], v[100:101], v[60:61]
	v_pk_add_f32 v[98:99], v[98:99], v[58:59]
	s_and_b64 vcc, exec, s[0:1]
	v_pk_add_f32 v[96:97], v[96:97], v[56:57]
	s_cbranch_vccnz .LBB0_218
	v_mul_f32_e32 v110, 0xbfb8aa3b, v101
	v_mul_f32_e32 v111, 0xbfb8aa3b, v97
	v_mul_f32_e32 v108, 0xbfb8aa3b, v100
	v_mul_f32_e32 v109, 0xbfb8aa3b, v96
	v_exp_f32_e32 v110, v110
	v_exp_f32_e32 v111, v111
	v_exp_f32_e32 v108, v108
	v_exp_f32_e32 v109, v109
	v_add_f32_e32 v110, 1.0, v110
	v_add_f32_e32 v111, 1.0, v111
	v_add_f32_e32 v108, 1.0, v108
	v_add_f32_e32 v109, 1.0, v109
	v_rcp_f32_e32 v110, v110
	v_mul_f32_e32 v112, 0xbfb8aa3b, v102
	v_mul_f32_e32 v113, 0xbfb8aa3b, v98
	v_rcp_f32_e32 v111, v111
	v_rcp_f32_e32 v108, v108
	v_rcp_f32_e32 v109, v109
	v_exp_f32_e32 v112, v112
	v_exp_f32_e32 v113, v113
	v_mul_f32_e32 v114, 0xbfb8aa3b, v103
	v_mul_f32_e32 v115, 0xbfb8aa3b, v99
	v_exp_f32_e32 v114, v114
	v_exp_f32_e32 v115, v115
	v_pk_fma_f32 v[110:111], v[110:111], s[24:25], 0.5 op_sel_hi:[1,0,0]
	v_add_f32_e32 v112, 1.0, v112
	v_add_f32_e32 v113, 1.0, v113
	v_pk_fma_f32 v[108:109], v[108:109], s[24:25], 0.5 op_sel_hi:[1,0,0]
	v_cvt_u32_f32_e32 v111, v111
	v_cvt_u32_f32_e32 v110, v110
	v_rcp_f32_e32 v112, v112
	v_rcp_f32_e32 v113, v113
	v_add_f32_e32 v114, 1.0, v114
	v_add_f32_e32 v115, 1.0, v115
	v_cvt_u32_f32_e32 v109, v109
	v_cvt_u32_f32_e32 v108, v108
	v_rcp_f32_e32 v114, v114
	v_rcp_f32_e32 v115, v115
	v_lshlrev_b32_e32 v111, 8, v111
	v_lshlrev_b32_e32 v110, 8, v110
	v_or_b32_e32 v111, v111, v109
	v_or_b32_e32 v110, v110, v108
	v_pk_fma_f32 v[108:109], v[112:113], s[24:25], 0.5 op_sel_hi:[1,0,0]
	s_nop 0
	v_cvt_u32_f32_sdwa v112, v108 dst_sel:WORD_1 dst_unused:UNUSED_PAD src0_sel:DWORD
	v_cvt_u32_f32_sdwa v113, v109 dst_sel:WORD_1 dst_unused:UNUSED_PAD src0_sel:DWORD
	v_pk_fma_f32 v[108:109], v[114:115], s[24:25], 0.5 op_sel_hi:[1,0,0]
	v_or_b32_e32 v110, v110, v112
	v_cvt_u32_f32_sdwa v109, v109 dst_sel:BYTE_3 dst_unused:UNUSED_PAD src0_sel:DWORD
	v_cvt_u32_f32_sdwa v108, v108 dst_sel:BYTE_3 dst_unused:UNUSED_PAD src0_sel:DWORD
	v_or_b32_e32 v111, v111, v113
	v_or_b32_e32 v109, v111, v109
	v_or_b32_e32 v108, v110, v108
	global_store_dwordx2 v[104:105], v[108:109], off offset:128 nt
	s_cbranch_execnz .LBB0_216

.LBB0_216:
	s_nop 1
	v_or_b32_e32 v100, 48, v162
	v_ashrrev_i32_e32 v101, 31, v100
	v_lshlrev_b64 v[102:103], 11, v[100:101]
	v_pk_add_f32 v[98:99], v[88:89], v[72:73]
	v_lshl_add_u64 v[88:89], s[14:15], 0, v[102:103]
	v_pk_add_f32 v[94:95], v[94:95], v[78:79]
	v_pk_add_f32 v[96:97], v[92:93], v[76:77]
	v_pk_add_f32 v[92:93], v[90:91], v[74:75]
	s_and_b64 vcc, exec, s[0:1]
	v_lshl_add_u64 v[88:89], v[88:89], 0, v[158:159]
	s_cbranch_vccnz .LBB0_219
	v_mul_f32_e32 v102, 0xbfb8aa3b, v97
	v_mul_f32_e32 v103, 0xbfb8aa3b, v99
	v_mul_f32_e32 v90, 0xbfb8aa3b, v96
	v_mul_f32_e32 v91, 0xbfb8aa3b, v98
	v_exp_f32_e32 v102, v102
	v_exp_f32_e32 v103, v103
	v_exp_f32_e32 v90, v90
	v_exp_f32_e32 v91, v91
	v_add_f32_e32 v102, 1.0, v102
	v_add_f32_e32 v103, 1.0, v103
	v_add_f32_e32 v90, 1.0, v90
	v_add_f32_e32 v91, 1.0, v91
	v_rcp_f32_e32 v102, v102
	v_mul_f32_e32 v104, 0xbfb8aa3b, v94
	v_mul_f32_e32 v105, 0xbfb8aa3b, v92
	v_rcp_f32_e32 v103, v103
	v_rcp_f32_e32 v90, v90
	v_rcp_f32_e32 v91, v91
	v_exp_f32_e32 v104, v104
	v_exp_f32_e32 v105, v105
	v_mul_f32_e32 v106, 0xbfb8aa3b, v95
	v_mul_f32_e32 v107, 0xbfb8aa3b, v93
	v_exp_f32_e32 v106, v106
	v_exp_f32_e32 v107, v107
	v_pk_fma_f32 v[102:103], v[102:103], s[24:25], 0.5 op_sel_hi:[1,0,0]
	v_add_f32_e32 v104, 1.0, v104
	v_add_f32_e32 v105, 1.0, v105
	v_pk_fma_f32 v[90:91], v[90:91], s[24:25], 0.5 op_sel_hi:[1,0,0]
	v_cvt_u32_f32_e32 v103, v103
	v_cvt_u32_f32_e32 v102, v102
	v_rcp_f32_e32 v104, v104
	v_rcp_f32_e32 v105, v105
	v_add_f32_e32 v106, 1.0, v106
	v_add_f32_e32 v107, 1.0, v107
	v_cvt_u32_f32_e32 v91, v91
	v_cvt_u32_f32_e32 v90, v90
	v_rcp_f32_e32 v106, v106
	v_rcp_f32_e32 v107, v107
	v_lshlrev_b32_e32 v103, 8, v103
	v_lshlrev_b32_e32 v102, 8, v102
	v_or_b32_e32 v103, v103, v91
	v_or_b32_e32 v102, v102, v90
	v_pk_fma_f32 v[90:91], v[104:105], s[24:25], 0.5 op_sel_hi:[1,0,0]
	s_mov_b64 s[40:41], 0
	v_cvt_u32_f32_sdwa v104, v90 dst_sel:WORD_1 dst_unused:UNUSED_PAD src0_sel:DWORD
	v_cvt_u32_f32_sdwa v105, v91 dst_sel:WORD_1 dst_unused:UNUSED_PAD src0_sel:DWORD
	v_pk_fma_f32 v[90:91], v[106:107], s[24:25], 0.5 op_sel_hi:[1,0,0]
	v_or_b32_e32 v102, v102, v104
	v_cvt_u32_f32_sdwa v91, v91 dst_sel:BYTE_3 dst_unused:UNUSED_PAD src0_sel:DWORD
	v_cvt_u32_f32_sdwa v90, v90 dst_sel:BYTE_3 dst_unused:UNUSED_PAD src0_sel:DWORD
	v_or_b32_e32 v103, v103, v105
	v_or_b32_e32 v91, v103, v91
	v_or_b32_e32 v90, v102, v90
	global_store_dwordx2 v[88:89], v[90:91], off nt
	s_branch .LBB0_220

.LBB0_222:
	v_pk_add_f32 v[86:87], v[86:87], v[62:63]
	v_pk_add_f32 v[84:85], v[84:85], v[60:61]
	v_pk_add_f32 v[82:83], v[82:83], v[58:59]
	s_and_b64 vcc, exec, s[0:1]
	v_pk_add_f32 v[80:81], v[80:81], v[56:57]
	s_cbranch_vccnz .LBB0_227
	v_mul_f32_e32 v94, 0xbfb8aa3b, v85
	v_mul_f32_e32 v95, 0xbfb8aa3b, v81
	v_mul_f32_e32 v92, 0xbfb8aa3b, v84
	v_mul_f32_e32 v93, 0xbfb8aa3b, v80
	v_exp_f32_e32 v94, v94
	v_exp_f32_e32 v95, v95
	v_exp_f32_e32 v92, v92
	v_exp_f32_e32 v93, v93
	v_add_f32_e32 v94, 1.0, v94
	v_add_f32_e32 v95, 1.0, v95
	v_add_f32_e32 v92, 1.0, v92
	v_add_f32_e32 v93, 1.0, v93
	v_rcp_f32_e32 v94, v94
	v_mul_f32_e32 v96, 0xbfb8aa3b, v86
	v_mul_f32_e32 v97, 0xbfb8aa3b, v82
	v_rcp_f32_e32 v95, v95
	v_rcp_f32_e32 v92, v92
	v_rcp_f32_e32 v93, v93
	v_exp_f32_e32 v96, v96
	v_exp_f32_e32 v97, v97
	v_mul_f32_e32 v98, 0xbfb8aa3b, v87
	v_mul_f32_e32 v99, 0xbfb8aa3b, v83
	v_exp_f32_e32 v98, v98
	v_exp_f32_e32 v99, v99
	v_pk_fma_f32 v[94:95], v[94:95], s[24:25], 0.5 op_sel_hi:[1,0,0]
	v_add_f32_e32 v96, 1.0, v96
	v_add_f32_e32 v97, 1.0, v97
	v_pk_fma_f32 v[92:93], v[92:93], s[24:25], 0.5 op_sel_hi:[1,0,0]
	v_cvt_u32_f32_e32 v95, v95
	v_cvt_u32_f32_e32 v94, v94
	v_rcp_f32_e32 v96, v96
	v_rcp_f32_e32 v97, v97
	v_add_f32_e32 v98, 1.0, v98
	v_add_f32_e32 v99, 1.0, v99
	v_cvt_u32_f32_e32 v93, v93
	v_cvt_u32_f32_e32 v92, v92
	v_rcp_f32_e32 v98, v98
	v_rcp_f32_e32 v99, v99
	v_lshlrev_b32_e32 v95, 8, v95
	v_lshlrev_b32_e32 v94, 8, v94
	v_or_b32_e32 v95, v95, v93
	v_or_b32_e32 v94, v94, v92
	v_pk_fma_f32 v[92:93], v[96:97], s[24:25], 0.5 op_sel_hi:[1,0,0]
	s_nop 0
	v_cvt_u32_f32_sdwa v96, v92 dst_sel:WORD_1 dst_unused:UNUSED_PAD src0_sel:DWORD
	v_cvt_u32_f32_sdwa v97, v93 dst_sel:WORD_1 dst_unused:UNUSED_PAD src0_sel:DWORD
	v_pk_fma_f32 v[92:93], v[98:99], s[24:25], 0.5 op_sel_hi:[1,0,0]
	v_or_b32_e32 v94, v94, v96
	v_cvt_u32_f32_sdwa v93, v93 dst_sel:BYTE_3 dst_unused:UNUSED_PAD src0_sel:DWORD
	v_cvt_u32_f32_sdwa v92, v92 dst_sel:BYTE_3 dst_unused:UNUSED_PAD src0_sel:DWORD
	v_or_b32_e32 v95, v95, v97
	v_or_b32_e32 v93, v95, v93
	v_or_b32_e32 v92, v94, v92
	global_store_dwordx2 v[88:89], v[92:93], off offset:128 nt
	s_cbranch_execnz .LBB0_225

.LBB0_225:
	s_nop 1
	v_add_u32_e32 v84, 0x80, v162
	v_ashrrev_i32_e32 v85, 31, v84
	v_lshlrev_b64 v[86:87], 11, v[84:85]
	v_pk_add_f32 v[82:83], v[64:65], v[72:73]
	v_lshl_add_u64 v[64:65], s[14:15], 0, v[86:87]
	v_pk_add_f32 v[70:71], v[70:71], v[78:79]
	v_pk_add_f32 v[80:81], v[68:69], v[76:77]
	v_pk_add_f32 v[68:69], v[66:67], v[74:75]
	s_and_b64 vcc, exec, s[0:1]
	v_lshl_add_u64 v[64:65], v[64:65], 0, v[158:159]
	s_cbranch_vccnz .LBB0_228
	v_mul_f32_e32 v86, 0xbfb8aa3b, v81
	v_mul_f32_e32 v87, 0xbfb8aa3b, v83
	v_mul_f32_e32 v66, 0xbfb8aa3b, v80
	v_mul_f32_e32 v67, 0xbfb8aa3b, v82
	v_exp_f32_e32 v86, v86
	v_exp_f32_e32 v87, v87
	v_exp_f32_e32 v66, v66
	v_exp_f32_e32 v67, v67
	v_add_f32_e32 v86, 1.0, v86
	v_add_f32_e32 v87, 1.0, v87
	v_add_f32_e32 v66, 1.0, v66
	v_add_f32_e32 v67, 1.0, v67
	v_rcp_f32_e32 v86, v86
	v_mul_f32_e32 v88, 0xbfb8aa3b, v70
	v_mul_f32_e32 v89, 0xbfb8aa3b, v68
	v_rcp_f32_e32 v87, v87
	v_rcp_f32_e32 v66, v66
	v_rcp_f32_e32 v67, v67
	v_exp_f32_e32 v88, v88
	v_exp_f32_e32 v89, v89
	v_mul_f32_e32 v90, 0xbfb8aa3b, v71
	v_mul_f32_e32 v91, 0xbfb8aa3b, v69
	v_exp_f32_e32 v90, v90
	v_exp_f32_e32 v91, v91
	v_pk_fma_f32 v[86:87], v[86:87], s[24:25], 0.5 op_sel_hi:[1,0,0]
	v_add_f32_e32 v88, 1.0, v88
	v_add_f32_e32 v89, 1.0, v89
	v_pk_fma_f32 v[66:67], v[66:67], s[24:25], 0.5 op_sel_hi:[1,0,0]
	v_cvt_u32_f32_e32 v87, v87
	v_cvt_u32_f32_e32 v86, v86
	v_rcp_f32_e32 v88, v88
	v_rcp_f32_e32 v89, v89
	v_add_f32_e32 v90, 1.0, v90
	v_add_f32_e32 v91, 1.0, v91
	v_cvt_u32_f32_e32 v67, v67
	v_cvt_u32_f32_e32 v66, v66
	v_rcp_f32_e32 v90, v90
	v_rcp_f32_e32 v91, v91
	v_lshlrev_b32_e32 v87, 8, v87
	v_lshlrev_b32_e32 v86, 8, v86
	v_or_b32_e32 v87, v87, v67
	v_or_b32_e32 v86, v86, v66
	v_pk_fma_f32 v[66:67], v[88:89], s[24:25], 0.5 op_sel_hi:[1,0,0]
	s_mov_b64 s[40:41], 0
	v_cvt_u32_f32_sdwa v88, v66 dst_sel:WORD_1 dst_unused:UNUSED_PAD src0_sel:DWORD
	v_cvt_u32_f32_sdwa v89, v67 dst_sel:WORD_1 dst_unused:UNUSED_PAD src0_sel:DWORD
	v_pk_fma_f32 v[66:67], v[90:91], s[24:25], 0.5 op_sel_hi:[1,0,0]
	v_or_b32_e32 v86, v86, v88
	v_cvt_u32_f32_sdwa v67, v67 dst_sel:BYTE_3 dst_unused:UNUSED_PAD src0_sel:DWORD
	v_cvt_u32_f32_sdwa v66, v66 dst_sel:BYTE_3 dst_unused:UNUSED_PAD src0_sel:DWORD
	v_or_b32_e32 v87, v87, v89
	v_or_b32_e32 v67, v87, v67
	v_or_b32_e32 v66, v86, v66
	global_store_dwordx2 v[64:65], v[66:67], off nt
	s_branch .LBB0_229

.LBB0_231:
	v_pk_add_f32 v[54:55], v[54:55], v[62:63]
	v_pk_add_f32 v[52:53], v[52:53], v[60:61]
	v_pk_add_f32 v[50:51], v[50:51], v[58:59]
	s_and_b64 vcc, exec, s[0:1]
	v_pk_add_f32 v[48:49], v[48:49], v[56:57]
	s_cbranch_vccnz .LBB0_236
	v_mul_f32_e32 v70, 0xbfb8aa3b, v53
	v_mul_f32_e32 v71, 0xbfb8aa3b, v49
	v_mul_f32_e32 v68, 0xbfb8aa3b, v52
	v_mul_f32_e32 v69, 0xbfb8aa3b, v48
	v_exp_f32_e32 v70, v70
	v_exp_f32_e32 v71, v71
	v_exp_f32_e32 v68, v68
	v_exp_f32_e32 v69, v69
	v_add_f32_e32 v70, 1.0, v70
	v_add_f32_e32 v71, 1.0, v71
	v_add_f32_e32 v68, 1.0, v68
	v_add_f32_e32 v69, 1.0, v69
	v_rcp_f32_e32 v70, v70
	v_mul_f32_e32 v80, 0xbfb8aa3b, v54
	v_mul_f32_e32 v81, 0xbfb8aa3b, v50
	v_rcp_f32_e32 v71, v71
	v_rcp_f32_e32 v68, v68
	v_rcp_f32_e32 v69, v69
	v_exp_f32_e32 v80, v80
	v_exp_f32_e32 v81, v81
	v_mul_f32_e32 v82, 0xbfb8aa3b, v55
	v_mul_f32_e32 v83, 0xbfb8aa3b, v51
	v_exp_f32_e32 v82, v82
	v_exp_f32_e32 v83, v83
	v_pk_fma_f32 v[70:71], v[70:71], s[24:25], 0.5 op_sel_hi:[1,0,0]
	v_add_f32_e32 v80, 1.0, v80
	v_add_f32_e32 v81, 1.0, v81
	v_pk_fma_f32 v[68:69], v[68:69], s[24:25], 0.5 op_sel_hi:[1,0,0]
	v_cvt_u32_f32_e32 v71, v71
	v_cvt_u32_f32_e32 v70, v70
	v_rcp_f32_e32 v80, v80
	v_rcp_f32_e32 v81, v81
	v_add_f32_e32 v82, 1.0, v82
	v_add_f32_e32 v83, 1.0, v83
	v_cvt_u32_f32_e32 v69, v69
	v_cvt_u32_f32_e32 v68, v68
	v_rcp_f32_e32 v82, v82
	v_rcp_f32_e32 v83, v83
	v_lshlrev_b32_e32 v71, 8, v71
	v_lshlrev_b32_e32 v70, 8, v70
	v_or_b32_e32 v71, v71, v69
	v_or_b32_e32 v70, v70, v68
	v_pk_fma_f32 v[68:69], v[80:81], s[24:25], 0.5 op_sel_hi:[1,0,0]
	s_nop 0
	v_cvt_u32_f32_sdwa v80, v68 dst_sel:WORD_1 dst_unused:UNUSED_PAD src0_sel:DWORD
	v_cvt_u32_f32_sdwa v81, v69 dst_sel:WORD_1 dst_unused:UNUSED_PAD src0_sel:DWORD
	v_pk_fma_f32 v[68:69], v[82:83], s[24:25], 0.5 op_sel_hi:[1,0,0]
	v_or_b32_e32 v70, v70, v80
	v_cvt_u32_f32_sdwa v69, v69 dst_sel:BYTE_3 dst_unused:UNUSED_PAD src0_sel:DWORD
	v_cvt_u32_f32_sdwa v68, v68 dst_sel:BYTE_3 dst_unused:UNUSED_PAD src0_sel:DWORD
	v_or_b32_e32 v71, v71, v81
	v_or_b32_e32 v69, v71, v69
	v_or_b32_e32 v68, v70, v68
	global_store_dwordx2 v[64:65], v[68:69], off offset:128 nt
	s_cbranch_execnz .LBB0_234

.LBB0_234:
	s_nop 1
	v_add_u32_e32 v52, 0x90, v162
	v_ashrrev_i32_e32 v53, 31, v52
	v_lshlrev_b64 v[54:55], 11, v[52:53]
	v_pk_add_f32 v[50:51], v[40:41], v[72:73]
	v_lshl_add_u64 v[40:41], s[14:15], 0, v[54:55]
	v_pk_add_f32 v[46:47], v[46:47], v[78:79]
	v_pk_add_f32 v[48:49], v[44:45], v[76:77]
	v_pk_add_f32 v[44:45], v[42:43], v[74:75]
	s_and_b64 vcc, exec, s[0:1]
	v_lshl_add_u64 v[40:41], v[40:41], 0, v[158:159]
	s_cbranch_vccnz .LBB0_237
	v_mul_f32_e32 v54, 0xbfb8aa3b, v49
	v_mul_f32_e32 v55, 0xbfb8aa3b, v51
	v_mul_f32_e32 v42, 0xbfb8aa3b, v48
	v_mul_f32_e32 v43, 0xbfb8aa3b, v50
	v_exp_f32_e32 v54, v54
	v_exp_f32_e32 v55, v55
	v_exp_f32_e32 v42, v42
	v_exp_f32_e32 v43, v43
	v_add_f32_e32 v54, 1.0, v54
	v_add_f32_e32 v55, 1.0, v55
	v_add_f32_e32 v42, 1.0, v42
	v_add_f32_e32 v43, 1.0, v43
	v_rcp_f32_e32 v54, v54
	v_mul_f32_e32 v64, 0xbfb8aa3b, v46
	v_mul_f32_e32 v65, 0xbfb8aa3b, v44
	v_rcp_f32_e32 v55, v55
	v_rcp_f32_e32 v42, v42
	v_rcp_f32_e32 v43, v43
	v_exp_f32_e32 v64, v64
	v_exp_f32_e32 v65, v65
	v_mul_f32_e32 v66, 0xbfb8aa3b, v47
	v_mul_f32_e32 v67, 0xbfb8aa3b, v45
	v_exp_f32_e32 v66, v66
	v_exp_f32_e32 v67, v67
	v_pk_fma_f32 v[54:55], v[54:55], s[24:25], 0.5 op_sel_hi:[1,0,0]
	v_add_f32_e32 v64, 1.0, v64
	v_add_f32_e32 v65, 1.0, v65
	v_pk_fma_f32 v[42:43], v[42:43], s[24:25], 0.5 op_sel_hi:[1,0,0]
	v_cvt_u32_f32_e32 v55, v55
	v_cvt_u32_f32_e32 v54, v54
	v_rcp_f32_e32 v64, v64
	v_rcp_f32_e32 v65, v65
	v_add_f32_e32 v66, 1.0, v66
	v_add_f32_e32 v67, 1.0, v67
	v_cvt_u32_f32_e32 v43, v43
	v_cvt_u32_f32_e32 v42, v42
	v_rcp_f32_e32 v66, v66
	v_rcp_f32_e32 v67, v67
	v_lshlrev_b32_e32 v55, 8, v55
	v_lshlrev_b32_e32 v54, 8, v54
	v_or_b32_e32 v55, v55, v43
	v_or_b32_e32 v54, v54, v42
	v_pk_fma_f32 v[42:43], v[64:65], s[24:25], 0.5 op_sel_hi:[1,0,0]
	s_mov_b64 s[40:41], 0
	v_cvt_u32_f32_sdwa v64, v42 dst_sel:WORD_1 dst_unused:UNUSED_PAD src0_sel:DWORD
	v_cvt_u32_f32_sdwa v65, v43 dst_sel:WORD_1 dst_unused:UNUSED_PAD src0_sel:DWORD
	v_pk_fma_f32 v[42:43], v[66:67], s[24:25], 0.5 op_sel_hi:[1,0,0]
	v_or_b32_e32 v54, v54, v64
	v_cvt_u32_f32_sdwa v43, v43 dst_sel:BYTE_3 dst_unused:UNUSED_PAD src0_sel:DWORD
	v_cvt_u32_f32_sdwa v42, v42 dst_sel:BYTE_3 dst_unused:UNUSED_PAD src0_sel:DWORD
	v_or_b32_e32 v55, v55, v65
	v_or_b32_e32 v43, v55, v43
	v_or_b32_e32 v42, v54, v42
	global_store_dwordx2 v[40:41], v[42:43], off nt
	s_branch .LBB0_238

.LBB0_240:
	v_pk_add_f32 v[38:39], v[38:39], v[62:63]
	v_pk_add_f32 v[36:37], v[36:37], v[60:61]
	v_pk_add_f32 v[34:35], v[34:35], v[58:59]
	s_and_b64 vcc, exec, s[0:1]
	v_pk_add_f32 v[32:33], v[32:33], v[56:57]
	s_cbranch_vccnz .LBB0_245
	v_mul_f32_e32 v46, 0xbfb8aa3b, v37
	v_mul_f32_e32 v47, 0xbfb8aa3b, v33
	v_mul_f32_e32 v44, 0xbfb8aa3b, v36
	v_mul_f32_e32 v45, 0xbfb8aa3b, v32
	v_exp_f32_e32 v46, v46
	v_exp_f32_e32 v47, v47
	v_exp_f32_e32 v44, v44
	v_exp_f32_e32 v45, v45
	v_add_f32_e32 v46, 1.0, v46
	v_add_f32_e32 v47, 1.0, v47
	v_add_f32_e32 v44, 1.0, v44
	v_add_f32_e32 v45, 1.0, v45
	v_rcp_f32_e32 v46, v46
	v_mul_f32_e32 v48, 0xbfb8aa3b, v38
	v_mul_f32_e32 v49, 0xbfb8aa3b, v34
	v_rcp_f32_e32 v47, v47
	v_rcp_f32_e32 v44, v44
	v_rcp_f32_e32 v45, v45
	v_exp_f32_e32 v48, v48
	v_exp_f32_e32 v49, v49
	v_mul_f32_e32 v50, 0xbfb8aa3b, v39
	v_mul_f32_e32 v51, 0xbfb8aa3b, v35
	v_exp_f32_e32 v50, v50
	v_exp_f32_e32 v51, v51
	v_pk_fma_f32 v[46:47], v[46:47], s[24:25], 0.5 op_sel_hi:[1,0,0]
	v_add_f32_e32 v48, 1.0, v48
	v_add_f32_e32 v49, 1.0, v49
	v_pk_fma_f32 v[44:45], v[44:45], s[24:25], 0.5 op_sel_hi:[1,0,0]
	v_cvt_u32_f32_e32 v47, v47
	v_cvt_u32_f32_e32 v46, v46
	v_rcp_f32_e32 v48, v48
	v_rcp_f32_e32 v49, v49
	v_add_f32_e32 v50, 1.0, v50
	v_add_f32_e32 v51, 1.0, v51
	v_cvt_u32_f32_e32 v45, v45
	v_cvt_u32_f32_e32 v44, v44
	v_rcp_f32_e32 v50, v50
	v_rcp_f32_e32 v51, v51
	v_lshlrev_b32_e32 v47, 8, v47
	v_lshlrev_b32_e32 v46, 8, v46
	v_or_b32_e32 v47, v47, v45
	v_or_b32_e32 v46, v46, v44
	v_pk_fma_f32 v[44:45], v[48:49], s[24:25], 0.5 op_sel_hi:[1,0,0]
	s_nop 0
	v_cvt_u32_f32_sdwa v48, v44 dst_sel:WORD_1 dst_unused:UNUSED_PAD src0_sel:DWORD
	v_cvt_u32_f32_sdwa v49, v45 dst_sel:WORD_1 dst_unused:UNUSED_PAD src0_sel:DWORD
	v_pk_fma_f32 v[44:45], v[50:51], s[24:25], 0.5 op_sel_hi:[1,0,0]
	v_or_b32_e32 v46, v46, v48
	v_cvt_u32_f32_sdwa v45, v45 dst_sel:BYTE_3 dst_unused:UNUSED_PAD src0_sel:DWORD
	v_cvt_u32_f32_sdwa v44, v44 dst_sel:BYTE_3 dst_unused:UNUSED_PAD src0_sel:DWORD
	v_or_b32_e32 v47, v47, v49
	v_or_b32_e32 v45, v47, v45
	v_or_b32_e32 v44, v46, v44
	global_store_dwordx2 v[40:41], v[44:45], off offset:128 nt
	s_cbranch_execnz .LBB0_243

.LBB0_243:
	s_nop 1
	v_add_u32_e32 v36, 0xa0, v162
	v_ashrrev_i32_e32 v37, 31, v36
	v_lshlrev_b64 v[38:39], 11, v[36:37]
	v_pk_add_f32 v[34:35], v[24:25], v[72:73]
	v_lshl_add_u64 v[24:25], s[14:15], 0, v[38:39]
	v_pk_add_f32 v[30:31], v[30:31], v[78:79]
	v_pk_add_f32 v[32:33], v[28:29], v[76:77]
	v_pk_add_f32 v[28:29], v[26:27], v[74:75]
	s_and_b64 vcc, exec, s[0:1]
	v_lshl_add_u64 v[24:25], v[24:25], 0, v[158:159]
	s_cbranch_vccnz .LBB0_246
	v_mul_f32_e32 v38, 0xbfb8aa3b, v33
	v_mul_f32_e32 v39, 0xbfb8aa3b, v35
	v_mul_f32_e32 v26, 0xbfb8aa3b, v32
	v_mul_f32_e32 v27, 0xbfb8aa3b, v34
	v_exp_f32_e32 v38, v38
	v_exp_f32_e32 v39, v39
	v_exp_f32_e32 v26, v26
	v_exp_f32_e32 v27, v27
	v_add_f32_e32 v38, 1.0, v38
	v_add_f32_e32 v39, 1.0, v39
	v_add_f32_e32 v26, 1.0, v26
	v_add_f32_e32 v27, 1.0, v27
	v_rcp_f32_e32 v38, v38
	v_mul_f32_e32 v40, 0xbfb8aa3b, v30
	v_mul_f32_e32 v41, 0xbfb8aa3b, v28
	v_rcp_f32_e32 v39, v39
	v_rcp_f32_e32 v26, v26
	v_rcp_f32_e32 v27, v27
	v_exp_f32_e32 v40, v40
	v_exp_f32_e32 v41, v41
	v_mul_f32_e32 v42, 0xbfb8aa3b, v31
	v_mul_f32_e32 v43, 0xbfb8aa3b, v29
	v_exp_f32_e32 v42, v42
	v_exp_f32_e32 v43, v43
	v_pk_fma_f32 v[38:39], v[38:39], s[24:25], 0.5 op_sel_hi:[1,0,0]
	v_add_f32_e32 v40, 1.0, v40
	v_add_f32_e32 v41, 1.0, v41
	v_pk_fma_f32 v[26:27], v[26:27], s[24:25], 0.5 op_sel_hi:[1,0,0]
	v_cvt_u32_f32_e32 v39, v39
	v_cvt_u32_f32_e32 v38, v38
	v_rcp_f32_e32 v40, v40
	v_rcp_f32_e32 v41, v41
	v_add_f32_e32 v42, 1.0, v42
	v_add_f32_e32 v43, 1.0, v43
	v_cvt_u32_f32_e32 v27, v27
	v_cvt_u32_f32_e32 v26, v26
	v_rcp_f32_e32 v42, v42
	v_rcp_f32_e32 v43, v43
	v_lshlrev_b32_e32 v39, 8, v39
	v_lshlrev_b32_e32 v38, 8, v38
	v_or_b32_e32 v39, v39, v27
	v_or_b32_e32 v38, v38, v26
	v_pk_fma_f32 v[26:27], v[40:41], s[24:25], 0.5 op_sel_hi:[1,0,0]
	s_mov_b64 s[40:41], 0
	v_cvt_u32_f32_sdwa v40, v26 dst_sel:WORD_1 dst_unused:UNUSED_PAD src0_sel:DWORD
	v_cvt_u32_f32_sdwa v41, v27 dst_sel:WORD_1 dst_unused:UNUSED_PAD src0_sel:DWORD
	v_pk_fma_f32 v[26:27], v[42:43], s[24:25], 0.5 op_sel_hi:[1,0,0]
	v_or_b32_e32 v38, v38, v40
	v_cvt_u32_f32_sdwa v27, v27 dst_sel:BYTE_3 dst_unused:UNUSED_PAD src0_sel:DWORD
	v_cvt_u32_f32_sdwa v26, v26 dst_sel:BYTE_3 dst_unused:UNUSED_PAD src0_sel:DWORD
	v_or_b32_e32 v39, v39, v41
	v_or_b32_e32 v27, v39, v27
	v_or_b32_e32 v26, v38, v26
	global_store_dwordx2 v[24:25], v[26:27], off nt
	s_branch .LBB0_247

.LBB0_249:
	v_pk_add_f32 v[22:23], v[22:23], v[62:63]
	v_pk_add_f32 v[20:21], v[20:21], v[60:61]
	v_pk_add_f32 v[18:19], v[18:19], v[58:59]
	s_and_b64 vcc, exec, s[0:1]
	v_pk_add_f32 v[16:17], v[16:17], v[56:57]
	s_cbranch_vccnz .LBB0_254
	v_mul_f32_e32 v30, 0xbfb8aa3b, v21
	v_mul_f32_e32 v31, 0xbfb8aa3b, v17
	v_mul_f32_e32 v28, 0xbfb8aa3b, v20
	v_mul_f32_e32 v29, 0xbfb8aa3b, v16
	v_exp_f32_e32 v30, v30
	v_exp_f32_e32 v31, v31
	v_exp_f32_e32 v28, v28
	v_exp_f32_e32 v29, v29
	v_add_f32_e32 v30, 1.0, v30
	v_add_f32_e32 v31, 1.0, v31
	v_add_f32_e32 v28, 1.0, v28
	v_add_f32_e32 v29, 1.0, v29
	v_rcp_f32_e32 v30, v30
	v_mul_f32_e32 v32, 0xbfb8aa3b, v22
	v_mul_f32_e32 v33, 0xbfb8aa3b, v18
	v_rcp_f32_e32 v31, v31
	v_rcp_f32_e32 v28, v28
	v_rcp_f32_e32 v29, v29
	v_exp_f32_e32 v32, v32
	v_exp_f32_e32 v33, v33
	v_mul_f32_e32 v34, 0xbfb8aa3b, v23
	v_mul_f32_e32 v35, 0xbfb8aa3b, v19
	v_exp_f32_e32 v34, v34
	v_exp_f32_e32 v35, v35
	v_pk_fma_f32 v[30:31], v[30:31], s[24:25], 0.5 op_sel_hi:[1,0,0]
	v_add_f32_e32 v32, 1.0, v32
	v_add_f32_e32 v33, 1.0, v33
	v_pk_fma_f32 v[28:29], v[28:29], s[24:25], 0.5 op_sel_hi:[1,0,0]
	v_cvt_u32_f32_e32 v31, v31
	v_cvt_u32_f32_e32 v30, v30
	v_rcp_f32_e32 v32, v32
	v_rcp_f32_e32 v33, v33
	v_add_f32_e32 v34, 1.0, v34
	v_add_f32_e32 v35, 1.0, v35
	v_cvt_u32_f32_e32 v29, v29
	v_cvt_u32_f32_e32 v28, v28
	v_rcp_f32_e32 v34, v34
	v_rcp_f32_e32 v35, v35
	v_lshlrev_b32_e32 v31, 8, v31
	v_lshlrev_b32_e32 v30, 8, v30
	v_or_b32_e32 v31, v31, v29
	v_or_b32_e32 v30, v30, v28
	v_pk_fma_f32 v[28:29], v[32:33], s[24:25], 0.5 op_sel_hi:[1,0,0]
	s_nop 0
	v_cvt_u32_f32_sdwa v32, v28 dst_sel:WORD_1 dst_unused:UNUSED_PAD src0_sel:DWORD
	v_cvt_u32_f32_sdwa v33, v29 dst_sel:WORD_1 dst_unused:UNUSED_PAD src0_sel:DWORD
	v_pk_fma_f32 v[28:29], v[34:35], s[24:25], 0.5 op_sel_hi:[1,0,0]
	v_or_b32_e32 v30, v30, v32
	v_cvt_u32_f32_sdwa v29, v29 dst_sel:BYTE_3 dst_unused:UNUSED_PAD src0_sel:DWORD
	v_cvt_u32_f32_sdwa v28, v28 dst_sel:BYTE_3 dst_unused:UNUSED_PAD src0_sel:DWORD
	v_or_b32_e32 v31, v31, v33
	v_or_b32_e32 v29, v31, v29
	v_or_b32_e32 v28, v30, v28
	global_store_dwordx2 v[24:25], v[28:29], off offset:128 nt
	s_cbranch_execnz .LBB0_252

.LBB0_252:
	s_nop 1
	v_add_u32_e32 v20, 0xb0, v162
	v_ashrrev_i32_e32 v21, 31, v20
	v_lshlrev_b64 v[22:23], 11, v[20:21]
	v_pk_add_f32 v[18:19], v[8:9], v[72:73]
	v_lshl_add_u64 v[8:9], s[14:15], 0, v[22:23]
	v_pk_add_f32 v[14:15], v[14:15], v[78:79]
	v_pk_add_f32 v[16:17], v[12:13], v[76:77]
	v_pk_add_f32 v[12:13], v[10:11], v[74:75]
	s_and_b64 vcc, exec, s[0:1]
	v_lshl_add_u64 v[8:9], v[8:9], 0, v[158:159]
	s_cbranch_vccnz .LBB0_255
	v_mul_f32_e32 v22, 0xbfb8aa3b, v17
	v_mul_f32_e32 v23, 0xbfb8aa3b, v19
	v_mul_f32_e32 v10, 0xbfb8aa3b, v16
	v_mul_f32_e32 v11, 0xbfb8aa3b, v18
	v_exp_f32_e32 v22, v22
	v_exp_f32_e32 v23, v23
	v_exp_f32_e32 v10, v10
	v_exp_f32_e32 v11, v11
	v_add_f32_e32 v22, 1.0, v22
	v_add_f32_e32 v23, 1.0, v23
	v_add_f32_e32 v10, 1.0, v10
	v_add_f32_e32 v11, 1.0, v11
	v_rcp_f32_e32 v22, v22
	v_mul_f32_e32 v24, 0xbfb8aa3b, v14
	v_mul_f32_e32 v25, 0xbfb8aa3b, v12
	v_rcp_f32_e32 v23, v23
	v_rcp_f32_e32 v10, v10
	v_rcp_f32_e32 v11, v11
	v_exp_f32_e32 v24, v24
	v_exp_f32_e32 v25, v25
	v_mul_f32_e32 v26, 0xbfb8aa3b, v15
	v_mul_f32_e32 v27, 0xbfb8aa3b, v13
	v_exp_f32_e32 v26, v26
	v_exp_f32_e32 v27, v27
	v_pk_fma_f32 v[22:23], v[22:23], s[24:25], 0.5 op_sel_hi:[1,0,0]
	v_add_f32_e32 v24, 1.0, v24
	v_add_f32_e32 v25, 1.0, v25
	v_pk_fma_f32 v[10:11], v[10:11], s[24:25], 0.5 op_sel_hi:[1,0,0]
	v_cvt_u32_f32_e32 v23, v23
	v_cvt_u32_f32_e32 v22, v22
	v_rcp_f32_e32 v24, v24
	v_rcp_f32_e32 v25, v25
	v_add_f32_e32 v26, 1.0, v26
	v_add_f32_e32 v27, 1.0, v27
	v_cvt_u32_f32_e32 v11, v11
	v_cvt_u32_f32_e32 v10, v10
	v_rcp_f32_e32 v26, v26
	v_rcp_f32_e32 v27, v27
	v_lshlrev_b32_e32 v23, 8, v23
	v_lshlrev_b32_e32 v22, 8, v22
	v_or_b32_e32 v23, v23, v11
	v_or_b32_e32 v22, v22, v10
	v_pk_fma_f32 v[10:11], v[24:25], s[24:25], 0.5 op_sel_hi:[1,0,0]
	s_mov_b64 s[40:41], 0
	v_cvt_u32_f32_sdwa v24, v10 dst_sel:WORD_1 dst_unused:UNUSED_PAD src0_sel:DWORD
	v_cvt_u32_f32_sdwa v25, v11 dst_sel:WORD_1 dst_unused:UNUSED_PAD src0_sel:DWORD
	v_pk_fma_f32 v[10:11], v[26:27], s[24:25], 0.5 op_sel_hi:[1,0,0]
	v_or_b32_e32 v22, v22, v24
	v_cvt_u32_f32_sdwa v11, v11 dst_sel:BYTE_3 dst_unused:UNUSED_PAD src0_sel:DWORD
	v_cvt_u32_f32_sdwa v10, v10 dst_sel:BYTE_3 dst_unused:UNUSED_PAD src0_sel:DWORD
	v_or_b32_e32 v23, v23, v25
	v_or_b32_e32 v11, v23, v11
	v_or_b32_e32 v10, v22, v10
	global_store_dwordx2 v[8:9], v[10:11], off nt
	s_branch .LBB0_256

.LBB0_258:
	v_pk_add_f32 v[6:7], v[6:7], v[62:63]
	v_pk_add_f32 v[4:5], v[4:5], v[60:61]
	v_pk_add_f32 v[2:3], v[2:3], v[58:59]
	s_and_b64 vcc, exec, s[0:1]
	v_pk_add_f32 v[0:1], v[0:1], v[56:57]
	s_cbranch_vccnz .LBB0_264
	v_mul_f32_e32 v14, 0xbfb8aa3b, v5
	v_mul_f32_e32 v15, 0xbfb8aa3b, v1
	v_mul_f32_e32 v12, 0xbfb8aa3b, v4
	v_mul_f32_e32 v13, 0xbfb8aa3b, v0
	v_exp_f32_e32 v14, v14
	v_exp_f32_e32 v15, v15
	v_exp_f32_e32 v12, v12
	v_exp_f32_e32 v13, v13
	v_add_f32_e32 v14, 1.0, v14
	v_add_f32_e32 v15, 1.0, v15
	v_add_f32_e32 v12, 1.0, v12
	v_add_f32_e32 v13, 1.0, v13
	v_rcp_f32_e32 v14, v14
	v_mul_f32_e32 v16, 0xbfb8aa3b, v6
	v_mul_f32_e32 v17, 0xbfb8aa3b, v2
	v_rcp_f32_e32 v15, v15
	v_rcp_f32_e32 v12, v12
	v_rcp_f32_e32 v13, v13
	v_exp_f32_e32 v16, v16
	v_exp_f32_e32 v17, v17
	v_mul_f32_e32 v18, 0xbfb8aa3b, v7
	v_mul_f32_e32 v19, 0xbfb8aa3b, v3
	v_exp_f32_e32 v18, v18
	v_exp_f32_e32 v19, v19
	v_pk_fma_f32 v[14:15], v[14:15], s[24:25], 0.5 op_sel_hi:[1,0,0]
	v_add_f32_e32 v16, 1.0, v16
	v_add_f32_e32 v17, 1.0, v17
	v_pk_fma_f32 v[12:13], v[12:13], s[24:25], 0.5 op_sel_hi:[1,0,0]
	v_cvt_u32_f32_e32 v15, v15
	v_cvt_u32_f32_e32 v14, v14
	v_rcp_f32_e32 v16, v16
	v_rcp_f32_e32 v17, v17
	v_add_f32_e32 v18, 1.0, v18
	v_add_f32_e32 v19, 1.0, v19
	v_cvt_u32_f32_e32 v13, v13
	v_cvt_u32_f32_e32 v12, v12
	v_rcp_f32_e32 v18, v18
	v_rcp_f32_e32 v19, v19
	v_lshlrev_b32_e32 v15, 8, v15
	v_lshlrev_b32_e32 v14, 8, v14
	v_or_b32_e32 v15, v15, v13
	v_or_b32_e32 v14, v14, v12
	v_pk_fma_f32 v[12:13], v[16:17], s[24:25], 0.5 op_sel_hi:[1,0,0]
	s_nop 0
	v_cvt_u32_f32_sdwa v16, v12 dst_sel:WORD_1 dst_unused:UNUSED_PAD src0_sel:DWORD
	v_cvt_u32_f32_sdwa v17, v13 dst_sel:WORD_1 dst_unused:UNUSED_PAD src0_sel:DWORD
	v_pk_fma_f32 v[12:13], v[18:19], s[24:25], 0.5 op_sel_hi:[1,0,0]
	v_or_b32_e32 v14, v14, v16
	v_cvt_u32_f32_sdwa v13, v13 dst_sel:BYTE_3 dst_unused:UNUSED_PAD src0_sel:DWORD
	v_cvt_u32_f32_sdwa v12, v12 dst_sel:BYTE_3 dst_unused:UNUSED_PAD src0_sel:DWORD
	v_or_b32_e32 v15, v15, v17
	v_or_b32_e32 v13, v15, v13
	v_or_b32_e32 v12, v14, v12
	global_store_dwordx2 v[8:9], v[12:13], off offset:128 nt
	s_cbranch_execnz .LBB0_261
